# speedup vs baseline: 1.0023x; 1.0023x over previous
; __device__ __forceinline__ unsigned cvtpk(float lo, float hi) { unsigned r; asm volatile("v_cvt_pk_bf16_f32 %0, %1, %2" : "=v"(r) : "v"(lo), "v"(hi)); return r; }
; __device__ __forceinline__ int crow(int r, int hi) { return (r & 3) + 8 * (r >> 2) + 4 * hi; }
; template <int LDQ, int LDK, int LDV, int LDO>
; __device__ __forceinline__ void attn256_body(const int tid, const bf16_t* __restrict__ Qb, const bf16_t* __restrict__ Kh, const bf16_t* __restrict__ Vh, bf16_t* __restrict__ Ob, int seq, char* lds, LAS unsigned char* ldsl) {
;     ...
;     if (hi == 0) li_l[r32] = l_reg; asm volatile("s_waitcnt lgkmcnt(0)" ::: "memory");
;     bf16_t* Ow = Ob + (long)(wid * 32) * LDO;
; #pragma unroll
;     for (int r = 0; r < 16; ++r) { const int orow = crow(r, hi); const float rl = __builtin_amdgcn_rcpf(li_l[orow]);
; #pragma unroll
;         for (int d0 = 0; d0 < 8; ++d0) Ow[(long)orow * LDO + d0 * 32 + r32] = (bf16_t)(cvtpk(o[d0][r] * rl, 0.f) & 0xffffu); }
.LBB0_143:
	s_and_saveexec_b64 s[0:1], s[4:5]
	ds_write_b32 v217, v146
	s_or_b64 exec, exec, s[0:1]
	s_mul_i32 s1, s30, 0x3800
	s_mul_hi_u32 s0, s30, 0x3800
	s_add_u32 s1, s93, s1
	s_waitcnt lgkmcnt(0)
	v_lshl_add_u32 v134, v210, 4, s17
	s_addc_u32 s0, s66, s0
	s_lshl_b32 s4, s15, 11
	ds_read_b128 v[224:227], v134
	ds_read_b128 v[228:231], v134 offset:32
	ds_read_b128 v[232:235], v134 offset:64
	ds_read_b128 v[236:239], v134 offset:96
	s_add_u32 s1, s1, s4
	s_addc_u32 s0, s0, 0
	s_lshl_b32 s4, s16, 1
	s_add_u32 s1, s1, s4
	s_addc_u32 s4, s0, 0
	s_mul_hi_i32 s5, s22, 0x3800
	s_mulk_i32 s22, 0x3800
	s_add_u32 s0, s1, s22
	s_waitcnt lgkmcnt(0)
	v_rcp_f32_e32 v135, v224
	s_addc_u32 s1, s4, s5
	v_lshlrev_b32_e32 v0, 1, v211
	v_lshl_add_u64 v[130:131], s[0:1], 0, v[0:1]
	s_mov_b64 s[0:1], 0x2000
	v_lshl_add_u64 v[130:131], v[130:131], 0, s[0:1]
	v_mul_u32_u24_e32 v0, 0xe000, v210
	v_lshl_add_u64 v[132:133], v[130:131], 0, v[0:1]
	v_mul_f32_e32 v0, v114, v135
	v_cvt_pk_bf16_f32 v0, v0, v1
	global_store_short v[132:133], v0, off
	v_mul_f32_e32 v0, v98, v135
	v_cvt_pk_bf16_f32 v0, v0, v1
	global_store_short v[132:133], v0, off offset:64
	v_mul_f32_e32 v0, v82, v135
	v_cvt_pk_bf16_f32 v0, v0, v1
	global_store_short v[132:133], v0, off offset:128
	v_mul_f32_e32 v0, v66, v135
	v_cvt_pk_bf16_f32 v0, v0, v1
	global_store_short v[132:133], v0, off offset:192
	v_mul_f32_e32 v0, v50, v135
	v_cvt_pk_bf16_f32 v0, v0, v1
	global_store_short v[132:133], v0, off offset:256
	v_mul_f32_e32 v0, v34, v135
	v_cvt_pk_bf16_f32 v0, v0, v1
	global_store_short v[132:133], v0, off offset:320
	v_mul_f32_e32 v0, v18, v135
	v_cvt_pk_bf16_f32 v0, v0, v1
	global_store_short v[132:133], v0, off offset:384
	v_mul_f32_e32 v0, v2, v135
	v_cvt_pk_bf16_f32 v0, v0, v1
	v_lshl_or_b32 v18, v210, 2, 1
	global_store_short v[132:133], v0, off offset:448
	v_mul_u32_u24_e32 v0, 0x3800, v18
	v_lshl_add_u64 v[132:133], v[130:131], 0, v[0:1]
	v_rcp_f32_e32 v2, v225
	s_mov_b64 s[0:1], 0
	v_mul_f32_e32 v0, v115, v2
	v_cvt_pk_bf16_f32 v0, v0, v1
	global_store_short v[132:133], v0, off
	v_mul_f32_e32 v0, v99, v2
	v_cvt_pk_bf16_f32 v0, v0, v1
	global_store_short v[132:133], v0, off offset:64
	v_mul_f32_e32 v0, v83, v2
	v_cvt_pk_bf16_f32 v0, v0, v1
	global_store_short v[132:133], v0, off offset:128
	v_mul_f32_e32 v0, v67, v2
	v_cvt_pk_bf16_f32 v0, v0, v1
	global_store_short v[132:133], v0, off offset:192
	v_mul_f32_e32 v0, v51, v2
	v_cvt_pk_bf16_f32 v0, v0, v1
	global_store_short v[132:133], v0, off offset:256
	v_mul_f32_e32 v0, v35, v2
	v_cvt_pk_bf16_f32 v0, v0, v1
	global_store_short v[132:133], v0, off offset:320
	v_mul_f32_e32 v0, v19, v2
	v_cvt_pk_bf16_f32 v0, v0, v1
	global_store_short v[132:133], v0, off offset:384
	v_mul_f32_e32 v0, v3, v2
	v_cvt_pk_bf16_f32 v0, v0, v1
	global_store_short v[132:133], v0, off offset:448
	v_mad_u32_u24 v0, v18, s44, s44
	v_rcp_f32_e32 v19, v226
	v_lshl_add_u64 v[2:3], v[130:131], 0, v[0:1]
	v_mul_f32_e32 v0, v116, v19
	v_cvt_pk_bf16_f32 v0, v0, v1
	global_store_short v[2:3], v0, off
	v_mul_f32_e32 v0, v100, v19
	v_cvt_pk_bf16_f32 v0, v0, v1
	global_store_short v[2:3], v0, off offset:64
	v_mul_f32_e32 v0, v84, v19
	v_cvt_pk_bf16_f32 v0, v0, v1
	global_store_short v[2:3], v0, off offset:128
	v_mul_f32_e32 v0, v68, v19
	v_cvt_pk_bf16_f32 v0, v0, v1
	global_store_short v[2:3], v0, off offset:192
	v_mul_f32_e32 v0, v52, v19
	v_cvt_pk_bf16_f32 v0, v0, v1
	global_store_short v[2:3], v0, off offset:256
	v_mul_f32_e32 v0, v36, v19
	v_cvt_pk_bf16_f32 v0, v0, v1
	global_store_short v[2:3], v0, off offset:320
	v_mul_f32_e32 v0, v20, v19
	v_cvt_pk_bf16_f32 v0, v0, v1
	global_store_short v[2:3], v0, off offset:384
	v_mul_f32_e32 v0, v4, v19
	v_cvt_pk_bf16_f32 v0, v0, v1
	global_store_short v[2:3], v0, off offset:448
	v_mov_b32_e32 v0, 0x7000
	v_mad_u32_u24 v0, v18, s44, v0
	v_lshl_add_u64 v[2:3], v[130:131], 0, v[0:1]
	v_rcp_f32_e32 v4, v227
	s_nop 0
	v_mul_f32_e32 v0, v117, v4
	v_cvt_pk_bf16_f32 v0, v0, v1
	global_store_short v[2:3], v0, off
	v_mul_f32_e32 v0, v101, v4
	v_cvt_pk_bf16_f32 v0, v0, v1
	global_store_short v[2:3], v0, off offset:64
	v_mul_f32_e32 v0, v85, v4
	v_cvt_pk_bf16_f32 v0, v0, v1
	global_store_short v[2:3], v0, off offset:128
	v_mul_f32_e32 v0, v69, v4
	v_cvt_pk_bf16_f32 v0, v0, v1
	global_store_short v[2:3], v0, off offset:192
	v_mul_f32_e32 v0, v53, v4
	v_cvt_pk_bf16_f32 v0, v0, v1
	global_store_short v[2:3], v0, off offset:256
	v_mul_f32_e32 v0, v37, v4
	v_cvt_pk_bf16_f32 v0, v0, v1
	global_store_short v[2:3], v0, off offset:320
	v_mul_f32_e32 v0, v21, v4
	v_cvt_pk_bf16_f32 v0, v0, v1
	global_store_short v[2:3], v0, off offset:384
	v_mul_f32_e32 v0, v5, v4
	v_cvt_pk_bf16_f32 v0, v0, v1
	global_store_short v[2:3], v0, off offset:448
	v_mov_b32_e32 v0, 0x18800
	v_mad_u32_u24 v0, v18, s44, v0
	v_lshl_add_u64 v[2:3], v[130:131], 0, v[0:1]
	v_rcp_f32_e32 v4, v228
	s_nop 0
	v_mul_f32_e32 v0, v118, v4
	v_cvt_pk_bf16_f32 v0, v0, v1
	global_store_short v[2:3], v0, off
	v_mul_f32_e32 v0, v102, v4
	v_cvt_pk_bf16_f32 v0, v0, v1
	global_store_short v[2:3], v0, off offset:64
	v_mul_f32_e32 v0, v86, v4
	v_cvt_pk_bf16_f32 v0, v0, v1
	global_store_short v[2:3], v0, off offset:128
	v_mul_f32_e32 v0, v70, v4
	v_cvt_pk_bf16_f32 v0, v0, v1
	global_store_short v[2:3], v0, off offset:192
	v_mul_f32_e32 v0, v54, v4
	v_cvt_pk_bf16_f32 v0, v0, v1
	global_store_short v[2:3], v0, off offset:256
	v_mul_f32_e32 v0, v38, v4
	v_cvt_pk_bf16_f32 v0, v0, v1
	global_store_short v[2:3], v0, off offset:320
	v_mul_f32_e32 v0, v22, v4
	v_cvt_pk_bf16_f32 v0, v0, v1
	global_store_short v[2:3], v0, off offset:384
	v_mul_f32_e32 v0, v6, v4
	v_cvt_pk_bf16_f32 v0, v0, v1
; __device__ __forceinline__ unsigned cvtpk(float lo, float hi) { unsigned r; asm volatile("v_cvt_pk_bf16_f32 %0, %1, %2" : "=v"(r) : "v"(lo), "v"(hi)); return r; }
; __device__ __forceinline__ int crow(int r, int hi) { return (r & 3) + 8 * (r >> 2) + 4 * hi; }
; template <int LDQ, int LDK, int LDV, int LDO>
; __device__ __forceinline__ void attn256_body(const int tid, const bf16_t* __restrict__ Qb, const bf16_t* __restrict__ Kh, const bf16_t* __restrict__ Vh, bf16_t* __restrict__ Ob, int seq, char* lds, LAS unsigned char* ldsl) {
;     ...
;     for (int r = 0; r < 16; ++r) { const int orow = crow(r, hi); const float rl = __builtin_amdgcn_rcpf(li_l[orow]);
; #pragma unroll
;         for (int d0 = 0; d0 < 8; ++d0) Ow[(long)orow * LDO + d0 * 32 + r32] = (bf16_t)(cvtpk(o[d0][r] * rl, 0.f) & 0xffffu); }
	global_store_short v[2:3], v0, off offset:448
	v_mov_b32_e32 v0, 0x1c000
	v_mad_u32_u24 v0, v18, s44, v0
	v_lshl_add_u64 v[2:3], v[130:131], 0, v[0:1]
	v_rcp_f32_e32 v4, v229
	s_nop 0
	v_mul_f32_e32 v0, v119, v4
	v_cvt_pk_bf16_f32 v0, v0, v1
	global_store_short v[2:3], v0, off
	v_mul_f32_e32 v0, v103, v4
	v_cvt_pk_bf16_f32 v0, v0, v1
	global_store_short v[2:3], v0, off offset:64
	v_mul_f32_e32 v0, v87, v4
	v_cvt_pk_bf16_f32 v0, v0, v1
	global_store_short v[2:3], v0, off offset:128
	v_mul_f32_e32 v0, v71, v4
	v_cvt_pk_bf16_f32 v0, v0, v1
	global_store_short v[2:3], v0, off offset:192
	v_mul_f32_e32 v0, v55, v4
	v_cvt_pk_bf16_f32 v0, v0, v1
	global_store_short v[2:3], v0, off offset:256
	v_mul_f32_e32 v0, v39, v4
	v_cvt_pk_bf16_f32 v0, v0, v1
	global_store_short v[2:3], v0, off offset:320
	v_mul_f32_e32 v0, v23, v4
	v_cvt_pk_bf16_f32 v0, v0, v1
	global_store_short v[2:3], v0, off offset:384
	v_mul_f32_e32 v0, v7, v4
	v_cvt_pk_bf16_f32 v0, v0, v1
	global_store_short v[2:3], v0, off offset:448
	v_mov_b32_e32 v0, 0x1f800
	v_mad_u32_u24 v0, v18, s44, v0
	v_lshl_add_u64 v[2:3], v[130:131], 0, v[0:1]
	v_rcp_f32_e32 v4, v230
	s_nop 0
	v_mul_f32_e32 v0, v120, v4
	v_cvt_pk_bf16_f32 v0, v0, v1
	global_store_short v[2:3], v0, off
	v_mul_f32_e32 v0, v104, v4
	v_cvt_pk_bf16_f32 v0, v0, v1
	global_store_short v[2:3], v0, off offset:64
	v_mul_f32_e32 v0, v88, v4
	v_cvt_pk_bf16_f32 v0, v0, v1
	global_store_short v[2:3], v0, off offset:128
	v_mul_f32_e32 v0, v72, v4
	v_cvt_pk_bf16_f32 v0, v0, v1
	global_store_short v[2:3], v0, off offset:192
	v_mul_f32_e32 v0, v56, v4
	v_cvt_pk_bf16_f32 v0, v0, v1
	global_store_short v[2:3], v0, off offset:256
	v_mul_f32_e32 v0, v40, v4
	v_cvt_pk_bf16_f32 v0, v0, v1
	global_store_short v[2:3], v0, off offset:320
	v_mul_f32_e32 v0, v24, v4
	v_cvt_pk_bf16_f32 v0, v0, v1
	global_store_short v[2:3], v0, off offset:384
	v_mul_f32_e32 v0, v8, v4
	v_cvt_pk_bf16_f32 v0, v0, v1
	global_store_short v[2:3], v0, off offset:448
	v_mov_b32_e32 v0, 0x23000
	v_mad_u32_u24 v0, v18, s44, v0
	v_lshl_add_u64 v[2:3], v[130:131], 0, v[0:1]
	v_rcp_f32_e32 v4, v231
	s_nop 0
	v_mul_f32_e32 v0, v121, v4
	v_cvt_pk_bf16_f32 v0, v0, v1
	global_store_short v[2:3], v0, off
	v_mul_f32_e32 v0, v105, v4
	v_cvt_pk_bf16_f32 v0, v0, v1
	global_store_short v[2:3], v0, off offset:64
	v_mul_f32_e32 v0, v89, v4
	v_cvt_pk_bf16_f32 v0, v0, v1
	global_store_short v[2:3], v0, off offset:128
	v_mul_f32_e32 v0, v73, v4
	v_cvt_pk_bf16_f32 v0, v0, v1
	global_store_short v[2:3], v0, off offset:192
	v_mul_f32_e32 v0, v57, v4
	v_cvt_pk_bf16_f32 v0, v0, v1
	global_store_short v[2:3], v0, off offset:256
	v_mul_f32_e32 v0, v41, v4
	v_cvt_pk_bf16_f32 v0, v0, v1
	global_store_short v[2:3], v0, off offset:320
	v_mul_f32_e32 v0, v25, v4
	v_cvt_pk_bf16_f32 v0, v0, v1
	global_store_short v[2:3], v0, off offset:384
	v_mul_f32_e32 v0, v9, v4
	v_cvt_pk_bf16_f32 v0, v0, v1
	global_store_short v[2:3], v0, off offset:448
	v_mov_b32_e32 v0, 0x34800
	v_mad_u32_u24 v0, v18, s44, v0
	v_lshl_add_u64 v[2:3], v[130:131], 0, v[0:1]
	v_rcp_f32_e32 v4, v232
	s_nop 0
	v_mul_f32_e32 v0, v122, v4
	v_cvt_pk_bf16_f32 v0, v0, v1
	global_store_short v[2:3], v0, off
	v_mul_f32_e32 v0, v106, v4
	v_cvt_pk_bf16_f32 v0, v0, v1
	global_store_short v[2:3], v0, off offset:64
	v_mul_f32_e32 v0, v90, v4
	v_cvt_pk_bf16_f32 v0, v0, v1
	global_store_short v[2:3], v0, off offset:128
	v_mul_f32_e32 v0, v74, v4
	v_cvt_pk_bf16_f32 v0, v0, v1
	global_store_short v[2:3], v0, off offset:192
	v_mul_f32_e32 v0, v58, v4
	v_cvt_pk_bf16_f32 v0, v0, v1
	global_store_short v[2:3], v0, off offset:256
	v_mul_f32_e32 v0, v42, v4
	v_cvt_pk_bf16_f32 v0, v0, v1
	global_store_short v[2:3], v0, off offset:320
	v_mul_f32_e32 v0, v26, v4
	v_cvt_pk_bf16_f32 v0, v0, v1
	global_store_short v[2:3], v0, off offset:384
	v_mul_f32_e32 v0, v10, v4
	v_cvt_pk_bf16_f32 v0, v0, v1
	global_store_short v[2:3], v0, off offset:448
	v_mov_b32_e32 v0, 0x38000
	v_mad_u32_u24 v0, v18, s44, v0
	v_lshl_add_u64 v[2:3], v[130:131], 0, v[0:1]
	v_rcp_f32_e32 v4, v233
	s_nop 0
	v_mul_f32_e32 v0, v123, v4
	v_cvt_pk_bf16_f32 v0, v0, v1
	global_store_short v[2:3], v0, off
	v_mul_f32_e32 v0, v107, v4
	v_cvt_pk_bf16_f32 v0, v0, v1
	global_store_short v[2:3], v0, off offset:64
	v_mul_f32_e32 v0, v91, v4
	v_cvt_pk_bf16_f32 v0, v0, v1
	global_store_short v[2:3], v0, off offset:128
	v_mul_f32_e32 v0, v75, v4
	v_cvt_pk_bf16_f32 v0, v0, v1
	global_store_short v[2:3], v0, off offset:192
	v_mul_f32_e32 v0, v59, v4
	v_cvt_pk_bf16_f32 v0, v0, v1
	global_store_short v[2:3], v0, off offset:256
	v_mul_f32_e32 v0, v43, v4
	v_cvt_pk_bf16_f32 v0, v0, v1
	global_store_short v[2:3], v0, off offset:320
	v_mul_f32_e32 v0, v27, v4
	v_cvt_pk_bf16_f32 v0, v0, v1
	global_store_short v[2:3], v0, off offset:384
	v_mul_f32_e32 v0, v11, v4
	v_cvt_pk_bf16_f32 v0, v0, v1
	global_store_short v[2:3], v0, off offset:448
	v_mov_b32_e32 v0, 0x3b800
	v_mad_u32_u24 v0, v18, s44, v0
	v_lshl_add_u64 v[2:3], v[130:131], 0, v[0:1]
	v_rcp_f32_e32 v4, v234
	s_nop 0
	v_mul_f32_e32 v0, v124, v4
	v_cvt_pk_bf16_f32 v0, v0, v1
	global_store_short v[2:3], v0, off
	v_mul_f32_e32 v0, v108, v4
	v_cvt_pk_bf16_f32 v0, v0, v1
	global_store_short v[2:3], v0, off offset:64
	v_mul_f32_e32 v0, v92, v4
	v_cvt_pk_bf16_f32 v0, v0, v1
	global_store_short v[2:3], v0, off offset:128
	v_mul_f32_e32 v0, v76, v4
; __device__ __forceinline__ unsigned cvtpk(float lo, float hi) { unsigned r; asm volatile("v_cvt_pk_bf16_f32 %0, %1, %2" : "=v"(r) : "v"(lo), "v"(hi)); return r; }
; __device__ __forceinline__ int crow(int r, int hi) { return (r & 3) + 8 * (r >> 2) + 4 * hi; }
; template <int LDQ, int LDK, int LDV, int LDO>
; __device__ __forceinline__ void attn256_body(const int tid, const bf16_t* __restrict__ Qb, const bf16_t* __restrict__ Kh, const bf16_t* __restrict__ Vh, bf16_t* __restrict__ Ob, int seq, char* lds, LAS unsigned char* ldsl) {
;     ...
;     for (int r = 0; r < 16; ++r) { const int orow = crow(r, hi); const float rl = __builtin_amdgcn_rcpf(li_l[orow]);
; #pragma unroll
;         for (int d0 = 0; d0 < 8; ++d0) Ow[(long)orow * LDO + d0 * 32 + r32] = (bf16_t)(cvtpk(o[d0][r] * rl, 0.f) & 0xffffu); }
;     __syncthreads();
	v_cvt_pk_bf16_f32 v0, v0, v1
	global_store_short v[2:3], v0, off offset:192
	v_mul_f32_e32 v0, v60, v4
	v_cvt_pk_bf16_f32 v0, v0, v1
	global_store_short v[2:3], v0, off offset:256
	v_mul_f32_e32 v0, v44, v4
	v_cvt_pk_bf16_f32 v0, v0, v1
	global_store_short v[2:3], v0, off offset:320
	v_mul_f32_e32 v0, v28, v4
	v_cvt_pk_bf16_f32 v0, v0, v1
	global_store_short v[2:3], v0, off offset:384
	v_mul_f32_e32 v0, v12, v4
	v_cvt_pk_bf16_f32 v0, v0, v1
	global_store_short v[2:3], v0, off offset:448
	v_mov_b32_e32 v0, 0x3f000
	v_mad_u32_u24 v0, v18, s44, v0
	v_lshl_add_u64 v[2:3], v[130:131], 0, v[0:1]
	v_rcp_f32_e32 v4, v235
	s_nop 0
	v_mul_f32_e32 v0, v125, v4
	v_cvt_pk_bf16_f32 v0, v0, v1
	global_store_short v[2:3], v0, off
	v_mul_f32_e32 v0, v109, v4
	v_cvt_pk_bf16_f32 v0, v0, v1
	global_store_short v[2:3], v0, off offset:64
	v_mul_f32_e32 v0, v93, v4
	v_cvt_pk_bf16_f32 v0, v0, v1
	global_store_short v[2:3], v0, off offset:128
	v_mul_f32_e32 v0, v77, v4
	v_cvt_pk_bf16_f32 v0, v0, v1
	global_store_short v[2:3], v0, off offset:192
	v_mul_f32_e32 v0, v61, v4
	v_cvt_pk_bf16_f32 v0, v0, v1
	global_store_short v[2:3], v0, off offset:256
	v_mul_f32_e32 v0, v45, v4
	v_cvt_pk_bf16_f32 v0, v0, v1
	global_store_short v[2:3], v0, off offset:320
	v_mul_f32_e32 v0, v29, v4
	v_cvt_pk_bf16_f32 v0, v0, v1
	global_store_short v[2:3], v0, off offset:384
	v_mul_f32_e32 v0, v13, v4
	v_cvt_pk_bf16_f32 v0, v0, v1
	global_store_short v[2:3], v0, off offset:448
	v_mov_b32_e32 v0, 0x50800
	v_mad_u32_u24 v0, v18, s44, v0
	v_lshl_add_u64 v[2:3], v[130:131], 0, v[0:1]
	v_rcp_f32_e32 v4, v236
	s_nop 0
	v_mul_f32_e32 v0, v126, v4
	v_cvt_pk_bf16_f32 v0, v0, v1
	global_store_short v[2:3], v0, off
	v_mul_f32_e32 v0, v110, v4
	v_cvt_pk_bf16_f32 v0, v0, v1
	global_store_short v[2:3], v0, off offset:64
	v_mul_f32_e32 v0, v94, v4
	v_cvt_pk_bf16_f32 v0, v0, v1
	global_store_short v[2:3], v0, off offset:128
	v_mul_f32_e32 v0, v78, v4
	v_cvt_pk_bf16_f32 v0, v0, v1
	global_store_short v[2:3], v0, off offset:192
	v_mul_f32_e32 v0, v62, v4
	v_cvt_pk_bf16_f32 v0, v0, v1
	global_store_short v[2:3], v0, off offset:256
	v_mul_f32_e32 v0, v46, v4
	v_cvt_pk_bf16_f32 v0, v0, v1
	global_store_short v[2:3], v0, off offset:320
	v_mul_f32_e32 v0, v30, v4
	v_cvt_pk_bf16_f32 v0, v0, v1
	global_store_short v[2:3], v0, off offset:384
	v_mul_f32_e32 v0, v14, v4
	v_cvt_pk_bf16_f32 v0, v0, v1
	global_store_short v[2:3], v0, off offset:448
	v_mov_b32_e32 v0, 0x54000
	v_mad_u32_u24 v0, v18, s44, v0
	v_lshl_add_u64 v[2:3], v[130:131], 0, v[0:1]
	v_rcp_f32_e32 v4, v237
	s_nop 0
	v_mul_f32_e32 v0, v127, v4
	v_cvt_pk_bf16_f32 v0, v0, v1
	global_store_short v[2:3], v0, off
	v_mul_f32_e32 v0, v111, v4
	v_cvt_pk_bf16_f32 v0, v0, v1
	global_store_short v[2:3], v0, off offset:64
	v_mul_f32_e32 v0, v95, v4
	v_cvt_pk_bf16_f32 v0, v0, v1
	global_store_short v[2:3], v0, off offset:128
	v_mul_f32_e32 v0, v79, v4
	v_cvt_pk_bf16_f32 v0, v0, v1
	global_store_short v[2:3], v0, off offset:192
	v_mul_f32_e32 v0, v63, v4
	v_cvt_pk_bf16_f32 v0, v0, v1
	global_store_short v[2:3], v0, off offset:256
	v_mul_f32_e32 v0, v47, v4
	v_cvt_pk_bf16_f32 v0, v0, v1
	global_store_short v[2:3], v0, off offset:320
	v_mul_f32_e32 v0, v31, v4
	v_cvt_pk_bf16_f32 v0, v0, v1
	global_store_short v[2:3], v0, off offset:384
	v_mul_f32_e32 v0, v15, v4
	v_cvt_pk_bf16_f32 v0, v0, v1
	global_store_short v[2:3], v0, off offset:448
	v_mov_b32_e32 v0, 0x57800
	v_mad_u32_u24 v0, v18, s44, v0
	v_lshl_add_u64 v[2:3], v[130:131], 0, v[0:1]
	v_rcp_f32_e32 v4, v238
	s_nop 0
	v_mul_f32_e32 v0, v128, v4
	v_cvt_pk_bf16_f32 v0, v0, v1
	global_store_short v[2:3], v0, off
	v_mul_f32_e32 v0, v112, v4
	v_cvt_pk_bf16_f32 v0, v0, v1
	global_store_short v[2:3], v0, off offset:64
	v_mul_f32_e32 v0, v96, v4
	v_cvt_pk_bf16_f32 v0, v0, v1
	global_store_short v[2:3], v0, off offset:128
	v_mul_f32_e32 v0, v80, v4
	v_cvt_pk_bf16_f32 v0, v0, v1
	global_store_short v[2:3], v0, off offset:192
	v_mul_f32_e32 v0, v64, v4
	v_cvt_pk_bf16_f32 v0, v0, v1
	global_store_short v[2:3], v0, off offset:256
	v_mul_f32_e32 v0, v48, v4
	v_cvt_pk_bf16_f32 v0, v0, v1
	global_store_short v[2:3], v0, off offset:320
	v_mul_f32_e32 v0, v32, v4
	v_cvt_pk_bf16_f32 v0, v0, v1
	global_store_short v[2:3], v0, off offset:384
	v_mul_f32_e32 v0, v16, v4
	v_cvt_pk_bf16_f32 v0, v0, v1
	global_store_short v[2:3], v0, off offset:448
	v_mov_b32_e32 v0, 0x5b000
	v_mad_u32_u24 v0, v18, s44, v0
	v_lshl_add_u64 v[2:3], v[130:131], 0, v[0:1]
	v_rcp_f32_e32 v4, v239
	s_nop 0
	v_mul_f32_e32 v0, v129, v4
	v_cvt_pk_bf16_f32 v0, v0, v1
	global_store_short v[2:3], v0, off
	v_mul_f32_e32 v0, v113, v4
	v_cvt_pk_bf16_f32 v0, v0, v1
	global_store_short v[2:3], v0, off offset:64
	v_mul_f32_e32 v0, v97, v4
	v_cvt_pk_bf16_f32 v0, v0, v1
	global_store_short v[2:3], v0, off offset:128
	v_mul_f32_e32 v0, v81, v4
	v_cvt_pk_bf16_f32 v0, v0, v1
	global_store_short v[2:3], v0, off offset:192
	v_mul_f32_e32 v0, v65, v4
	v_cvt_pk_bf16_f32 v0, v0, v1
	global_store_short v[2:3], v0, off offset:256
	v_mul_f32_e32 v0, v49, v4
	v_cvt_pk_bf16_f32 v0, v0, v1
	global_store_short v[2:3], v0, off offset:320
	v_mul_f32_e32 v0, v33, v4
	v_cvt_pk_bf16_f32 v0, v0, v1
	global_store_short v[2:3], v0, off offset:384
	v_mul_f32_e32 v0, v17, v4
	v_cvt_pk_bf16_f32 v0, v0, v1
	global_store_short v[2:3], v0, off offset:448
	s_barrier
